# grid barriers skipped at the four seams without a data dependency (memory K/V projection -> prep of group 0; final norm of group g -> prep of group g+1)
# speedup vs baseline: 1.0007x; 1.0007x over previous
; __global__ void __launch_bounds__(NT_THREADS) k_mega(Params p) {
;     ...
;   for (int ph = 0; ph < NPHASES; ++ph) {
;     run_phase(p, ph, lds);
;     if (DUP_MASK && ph >= 2 && ((DUP_MASK >> ((ph - 2) % 11)) & 1)) { grid.sync(); run_phase(p, ph, lds, DUP_SEL); }
;     if ((DUP_MASK & 0x8000) && ph == 0) { for (int rep = 0; rep < 3; ++rep) { grid.sync(); run_phase(p, ph, lds, DUP_SEL); } }
;     if (ph + 1 < NPHASES) { if (ph == 0) grid.sync(); else xcd_barrier(xb); }
.LBB0_523:
	s_cmp_eq_u32 s81, 1
	s_cbranch_scc1 .LBB0_594
	s_cmp_eq_u32 s81, 12
	s_cbranch_scc1 .LBB0_594
	s_cmp_eq_u32 s81, 23
	s_cbranch_scc1 .LBB0_594
	s_cmp_eq_u32 s81, 34
	s_cbranch_scc1 .LBB0_594
	s_mov_b64 s[14:15], -1
	s_mov_b64 s[0:1], 0
	s_cmp_lt_i32 s81, 45
	s_mov_b64 s[4:5], 0
	s_cbranch_scc1 .LBB0_537
	s_cmp_lg_u32 s81, 45
	s_cselect_b64 s[4:5], -1, 0
	s_cbranch_execz .LBB0_538
